# v17: mLSTM C-update - k^T fragments of tile groups 2 and 3 read early into dead registers with counted lgkmcnt waits (on top of v16)
# baseline (speedup 1.0000x reference)
; #define LAS __attribute__((address_space(3)))
; template <int SKIP>
; DEV void mlstm_phase(LAS char* shm, const bf16_t* q, const bf16_t* k, const bf16_t* v, const float* gpart, const float* b_ig, const float* b_fg, bf16_t* hc, const bool pre) {
;     ...
;             if (!(SKIP & 4)) {
;                 const float decay = __expf(m_prev - mxc);
; #pragma unroll
;                 for (int i = 0; i < 3; ++i)
; #pragma unroll
;                     for (int vt = 0; vt < 3; ++vt) cacc[i][vt] *= decay;
;                 const int q_ = fr >> 2, p_ = fr & 3;
;                 s16x4 wl[2][3], wh[2][3];
; #pragma unroll
;                 for (int kk = 0; kk < 2; ++kk)
; #pragma unroll
;                     for (int vt = 0; vt < 3; ++vt) {
;                         wl[kk][vt] = __builtin_amdgcn_ds_read_tr16_b64_v4i16((LAS s16x4*)(shm + VWT + (32 * kk + 8 * fq + q_) * VRS + (16 * vt + 4 * p_) * 2));
;                         wh[kk][vt] = __builtin_amdgcn_ds_read_tr16_b64_v4i16((LAS s16x4*)(shm + VWT + (32 * kk + 8 * fq + 4 + q_) * VRS + (16 * vt + 4 * p_) * 2));
;                     }
;                 bf16x8 bfv[2][3];
; #pragma unroll
;                 for (int kk = 0; kk < 2; ++kk)
; #pragma unroll
;                     for (int vt = 0; vt < 3; ++vt) { bfv[kk][vt][0] = wl[kk][vt][0]; bfv[kk][vt][1] = wl[kk][vt][1]; bfv[kk][vt][2] = wl[kk][vt][2]; bfv[kk][vt][3] = wl[kk][vt][3];
;                         bfv[kk][vt][4] = wh[kk][vt][0]; bfv[kk][vt][5] = wh[kk][vt][1]; bfv[kk][vt][6] = wh[kk][vt][2]; bfv[kk][vt][7] = wh[kk][vt][3]; }
;                 const int rl_ = 8 * fq + q_, rh_ = rl_ + 4;
; #pragma unroll
;                 for (int i = 0; i < 3; ++i) {
;                     if (i < ndt) {
;                         const int un = 2 * (dt0 + i) + (p_ >> 1);
;                         s16x4 kl[2], kh[2];
; #pragma unroll
;                         for (int kk = 0; kk < 2; ++kk) {
;                             kl[kk] = __builtin_amdgcn_ds_read_tr16_b64_v4i16((LAS s16x4*)(kbuf + (32 * kk + rl_) * 512 + ((un ^ (rl_ & 15)) << 4) + (p_ & 1) * 8));
;                             kh[kk] = __builtin_amdgcn_ds_read_tr16_b64_v4i16((LAS s16x4*)(kbuf + (32 * kk + rh_) * 512 + ((un ^ (rh_ & 15)) << 4) + (p_ & 1) * 8));
;                         }
; #pragma unroll
;                         for (int kk = 0; kk < 2; ++kk) {
.LBB0_664:
	v_mov_b32_e32 v0, s43
	v_sub_f32_e32 v0, s28, v0
	v_mul_f32_e32 v0, 0x3fb8aa3b, v0
	v_exp_f32_e32 v4, v0
	v_add_u32_e32 v34, s29, v190
	v_add_u32_e32 v0, v34, v220
	v_add3_u32 v1, v34, v167, v193
	v_pk_mul_f32 v[68:69], v[68:69], v[4:5] op_sel_hi:[1,0]
	v_pk_mul_f32 v[66:67], v[66:67], v[4:5] op_sel_hi:[1,0]
	v_pk_mul_f32 v[64:65], v[64:65], v[4:5] op_sel_hi:[1,0]
	v_add_u32_e32 v5, v0, v194
	s_nop 0
	ds_read_b64_tr_b16 v[22:23], v1
	ds_read_b64_tr_b16 v[24:25], v5
	ds_read_b64_tr_b16 v[28:29], v210 offset:384
	ds_read_b64_tr_b16 v[26:27], v210
	ds_read_b64_tr_b16 v[30:31], v210 offset:32
	ds_read_b64_tr_b16 v[18:19], v210 offset:64
	v_pk_mul_f32 v[12:13], v[52:53], v[4:5] op_sel_hi:[1,0]
	v_pk_mul_f32 v[10:11], v[50:51], v[4:5] op_sel_hi:[1,0]
	v_add_u32_e32 v0, v0, v193
	ds_read_b64_tr_b16 v[38:39], v0 offset:18432
	ds_read_b64_tr_b16 v[36:37], v1 offset:16384
	s_waitcnt lgkmcnt(0)
	v_mfma_f32_16x16x32_bf16 v[50:53], v[22:25], v[26:29], v[10:13]
	ds_read_b64_tr_b16 v[32:33], v210 offset:416
	ds_read_b64_tr_b16 v[20:21], v210 offset:448
	ds_read_b64_tr_b16 v[14:15], v210 offset:3072
	ds_read_b64_tr_b16 v[10:11], v210 offset:3104
	v_pk_mul_f32 v[48:49], v[48:49], v[4:5] op_sel_hi:[1,0]
	v_pk_mul_f32 v[46:47], v[46:47], v[4:5] op_sel_hi:[1,0]
	v_pk_mul_f32 v[44:45], v[44:45], v[4:5] op_sel_hi:[1,0]
	v_pk_mul_f32 v[42:43], v[42:43], v[4:5] op_sel_hi:[1,0]
	s_waitcnt lgkmcnt(3)
	v_mfma_f32_16x16x32_bf16 v[46:49], v[22:25], v[30:33], v[46:49]
	ds_read_b64_tr_b16 v[16:17], v210 offset:3456
	v_cndmask_b32_e64 v0, 0, 1, s[34:35]
	v_pk_mul_f32 v[62:63], v[62:63], v[4:5] op_sel_hi:[1,0]
	s_waitcnt lgkmcnt(3)
	v_mfma_f32_16x16x32_bf16 v[40:43], v[22:25], v[18:21], v[42:45]
	ds_read_b64_tr_b16 v[12:13], v210 offset:3488
	ds_read_b64_tr_b16 v[24:25], v210 offset:3520
	ds_read_b64_tr_b16 v[22:23], v210 offset:3136
	v_add_u32_e32 v142, v34, v222
	v_add3_u32 v143, v34, v221, v193
	v_add_u32_e32 v144, v142, v194
	v_add_u32_e32 v142, v142, v193
	ds_read_b64_tr_b16 v[126:127], v143
	ds_read_b64_tr_b16 v[128:129], v144
	ds_read_b64_tr_b16 v[130:131], v143 offset:16384
	ds_read_b64_tr_b16 v[132:133], v142 offset:18432
	v_add_u32_e32 v145, v34, v224
	v_add3_u32 v146, v34, v223, v193
	v_add_u32_e32 v147, v145, v194
	v_add_u32_e32 v145, v145, v193
	ds_read_b64_tr_b16 v[134:135], v146
	ds_read_b64_tr_b16 v[136:137], v147
	ds_read_b64_tr_b16 v[138:139], v146 offset:16384
	ds_read_b64_tr_b16 v[140:141], v145 offset:18432
	v_pk_mul_f32 v[56:57], v[56:57], v[4:5] op_sel_hi:[1,0]
	v_pk_mul_f32 v[54:55], v[54:55], v[4:5] op_sel_hi:[1,0]
	s_waitcnt lgkmcnt(11)
	v_mfma_f32_16x16x32_bf16 v[50:53], v[36:39], v[14:17], v[50:53]
	v_cmp_ne_u32_e64 s[28:29], 1, v0
	s_andn2_b64 vcc, exec, s[34:35]
	s_waitcnt lgkmcnt(10)
	v_mfma_f32_16x16x32_bf16 v[46:49], v[36:39], v[10:13], v[46:49]
	s_waitcnt lgkmcnt(8)
	v_mfma_f32_16x16x32_bf16 v[42:45], v[36:39], v[22:25], v[40:43]
	s_cbranch_vccnz .LBB0_666
	s_nop 0
	s_waitcnt lgkmcnt(6)
	v_mfma_f32_16x16x32_bf16 v[66:69], v[126:129], v[26:29], v[66:69]
	v_mfma_f32_16x16x32_bf16 v[62:65], v[126:129], v[30:33], v[62:65]
	v_mfma_f32_16x16x32_bf16 v[36:39], v[126:129], v[18:21], v[54:57]
	s_waitcnt lgkmcnt(4)
	v_mfma_f32_16x16x32_bf16 v[66:69], v[130:133], v[14:17], v[66:69]
	v_mfma_f32_16x16x32_bf16 v[62:65], v[130:133], v[10:13], v[62:65]
	v_mfma_f32_16x16x32_bf16 v[54:57], v[130:133], v[22:25], v[36:39]
.LBB0_666:
	v_mov_b32_e32 v0, v4
	v_mov_b32_e32 v1, v4
	v_mov_b32_e32 v5, v4
	v_pk_mul_f32 v[72:73], v[72:73], v[0:1]
	v_pk_mul_f32 v[76:77], v[76:77], v[0:1]
	v_pk_mul_f32 v[60:61], v[60:61], v[0:1]
	v_cndmask_b32_e64 v0, 0, 1, s[36:37]
	v_pk_mul_f32 v[70:71], v[70:71], v[4:5]
	v_pk_mul_f32 v[74:75], v[74:75], v[4:5]
	v_cmp_ne_u32_e64 s[30:31], 1, v0
	s_andn2_b64 vcc, exec, s[36:37]
	v_pk_mul_f32 v[58:59], v[58:59], v[4:5]
	s_cbranch_vccnz .LBB0_668
	s_nop 0
	s_waitcnt lgkmcnt(2)
	v_mfma_f32_16x16x32_bf16 v[26:29], v[134:137], v[26:29], v[70:73]
	v_mfma_f32_16x16x32_bf16 v[30:33], v[134:137], v[30:33], v[74:77]
	v_mfma_f32_16x16x32_bf16 v[18:21], v[134:137], v[18:21], v[58:61]
	s_waitcnt lgkmcnt(0)
	v_mfma_f32_16x16x32_bf16 v[70:73], v[138:141], v[14:17], v[26:29]
	v_mfma_f32_16x16x32_bf16 v[74:77], v[138:141], v[10:13], v[30:33]
	v_mfma_f32_16x16x32_bf16 v[58:61], v[138:141], v[22:25], v[18:21]
